# final-norm loops: gamma chunks loaded once before the row loop (16 VGPRs), per-chunk load+vmcnt(0) after each nt store removed
# speedup vs baseline: 1.0018x; 1.0018x over previous
; __device__ __forceinline__ int otid(int wv) { (void)wv; int t = threadIdx.x; asm volatile("" : "+v"(t)); return t; }
; __device__ __forceinline__ void final_phase(const Args& a, int wv, int row_lo, int row_hi, int bidx, int nblk) {
;     const int tid_ = otid(wv); const int lane = tid_ & 63, wid = tid_ >> 6;
;     const float* g = a.in[32];
;     const int nw = nblk * 8;
;     const int MT = row_hi;
;     for (int rb = row_lo + bidx * 8 + wid; rb < MT; rb += nw * 4) {
;     ...
;                 for (int i = 0; i < 4; ++i) { const int c = i * 256 + lane * 4; const f32x4 g4 = *(const f32x4*)(g + c); __builtin_nontemporal_store(v[j][i] * rstd * g4, (f32x4*)(x + c)); }
.LBB0_1973:
	s_cmp_lt_i32 s84, 22
	s_cselect_b64 s[0:1], -1, 0
	s_cmp_gt_i32 s85, 21
	s_cselect_b64 s[2:3], -1, 0
	s_and_b64 s[0:1], s[0:1], s[2:3]
	v_readlane_b32 s42, v255, 16
	s_and_b64 vcc, exec, s[0:1]
	v_readlane_b32 s43, v255, 17
	s_cbranch_vccz .LBB0_2045
	v_readlane_b32 s4, v251, 31
	s_cmpk_lt_i32 s16, 0xf8
	v_readlane_b32 s5, v251, 32
	s_cselect_b64 s[2:3], -1, 0
	s_xor_b64 s[4:5], s[4:5], -1
	s_or_b64 s[2:3], s[2:3], s[4:5]
	s_mov_b64 s[0:1], -1
	s_and_b64 vcc, exec, s[2:3]
	s_cbranch_vccz .LBB0_2010
	s_load_dwordx4 s[12:15], s[42:43], 0x100
	v_readlane_b32 s2, v251, 51
	v_readlane_b32 s3, v251, 52
	v_readlane_b32 s22, v254, 15
	s_and_b64 vcc, exec, s[2:3]
	v_readlane_b32 s23, v254, 16
	s_cbranch_vccz .LBB0_1992
	v_mov_b32_e32 v0, v215
	s_mov_b32 s10, 0x10200
	s_waitcnt lgkmcnt(0)
	v_ashrrev_i32_e32 v1, 6, v0
	v_add_u32_e32 v70, s22, v1
	v_cmp_gt_i32_e32 vcc, s10, v70
	s_and_saveexec_b64 s[0:1], vcc
	s_cbranch_execz .LBB0_1991
	v_and_b32_e32 v2, 64, v248
	v_add_u32_e32 v2, 64, v2
	v_xor_b32_e32 v3, 32, v248
	v_cmp_lt_i32_e32 vcc, v3, v2
	v_lshlrev_b32_e32 v0, 4, v0
	v_and_b32_e32 v0, 0x3f0, v0
	v_cndmask_b32_e32 v3, v248, v3, vcc
	v_lshlrev_b32_e32 v76, 2, v3
	v_xor_b32_e32 v3, 16, v248
	v_cmp_lt_i32_e32 vcc, v3, v2
	v_mov_b32_e32 v1, 0
	s_add_i32 s17, s34, s34
	v_cndmask_b32_e32 v3, v248, v3, vcc
	v_lshlrev_b32_e32 v77, 2, v3
	v_xor_b32_e32 v3, 8, v248
	v_cmp_lt_i32_e32 vcc, v3, v2
	v_lshl_add_u64 v[64:65], s[14:15], 0, v[0:1]
	v_lshl_add_u64 v[66:67], s[12:13], 0, v[0:1]
	global_load_dwordx4 v[232:235], v[66:67], off
	global_load_dwordx4 v[236:239], v[66:67], off offset:1024
	global_load_dwordx4 v[240:243], v[66:67], off offset:2048
	global_load_dwordx4 v[244:247], v[66:67], off offset:3072
	v_cndmask_b32_e32 v3, v248, v3, vcc
	v_lshlrev_b32_e32 v78, 2, v3
	v_xor_b32_e32 v3, 4, v248
	v_cmp_lt_i32_e32 vcc, v3, v2
	s_mov_b64 s[2:3], 0
	v_mov_b32_e32 v82, 0x358637bd
	v_cndmask_b32_e32 v3, v248, v3, vcc
	v_lshlrev_b32_e32 v79, 2, v3
	v_xor_b32_e32 v3, 2, v248
	v_cmp_lt_i32_e32 vcc, v3, v2
	s_mov_b32 s11, 0x800000
	s_add_i32 s17, s17, s34
	v_cndmask_b32_e32 v3, v248, v3, vcc
	v_lshlrev_b32_e32 v80, 2, v3
	v_xor_b32_e32 v3, 1, v248
	v_cmp_lt_i32_e32 vcc, v3, v2
	s_mov_b32 s18, 0x101ff
	s_nop 0
	v_cndmask_b32_e32 v2, v248, v3, vcc
	v_lshlrev_b32_e32 v81, 2, v2
	s_branch .LBB0_1979

; __device__ __forceinline__ void final_phase(const Args& a, int wv, int row_lo, int row_hi, int bidx, int nblk) {
;     ...
; #pragma unroll
;         for (int j = 0; j < 4; ++j) {
;             const int row = rb + j * nw;
;             if (row < MT) {
;                 float* x = a.out + (size_t)row * DM;
;                 float ss = 0.f;
; #pragma unroll
;                 for (int i = 0; i < 4; ++i) ss += v[j][i][0] * v[j][i][0] + v[j][i][1] * v[j][i][1] + v[j][i][2] * v[j][i][2] + v[j][i][3] * v[j][i][3];
;                 ss = wave_sum(ss);
;                 const float rstd = rsqrtf(ss * (1.f / 1024.f) + EPS);
; #pragma unroll
;                 for (int i = 0; i < 4; ++i) { const int c = i * 256 + lane * 4; const f32x4 g4 = *(const f32x4*)(g + c); __builtin_nontemporal_store(v[j][i] * rstd * g4, (f32x4*)(x + c)); }
;             }
.LBB0_1985:
	s_or_b64 exec, exec, s[8:9]
	s_waitcnt vmcnt(0)
	v_mov_b32_e32 v90, v61
	v_mov_b32_e32 v91, v57
	v_mov_b32_e32 v88, v60
	v_mov_b32_e32 v89, v56
	v_mov_b32_e32 v98, v53
	v_mov_b32_e32 v99, v49
	v_pk_mul_f32 v[90:91], v[90:91], v[90:91]
	v_mov_b32_e32 v92, v62
	v_mov_b32_e32 v93, v58
	v_mov_b32_e32 v96, v52
	v_mov_b32_e32 v97, v48
	v_pk_mul_f32 v[98:99], v[98:99], v[98:99]
	v_pk_fma_f32 v[88:89], v[88:89], v[88:89], v[90:91]
	v_mov_b32_e32 v94, v63
	v_mov_b32_e32 v95, v59
	v_mov_b32_e32 v100, v54
	v_mov_b32_e32 v101, v50
	v_pk_fma_f32 v[90:91], v[96:97], v[96:97], v[98:99]
	v_pk_fma_f32 v[88:89], v[92:93], v[92:93], v[88:89]
	v_mov_b32_e32 v102, v55
	v_mov_b32_e32 v103, v51
	v_pk_fma_f32 v[90:91], v[100:101], v[100:101], v[90:91]
	v_pk_fma_f32 v[88:89], v[94:95], v[94:95], v[88:89]
	v_pk_fma_f32 v[90:91], v[102:103], v[102:103], v[90:91]
	v_add_f32_e32 v83, v88, v89
	v_add_f32_e32 v83, v83, v90
	v_add_f32_e32 v83, v83, v91
	ds_bpermute_b32 v88, v76, v83
	s_waitcnt lgkmcnt(0)
	v_add_f32_e32 v83, v83, v88
	ds_bpermute_b32 v88, v77, v83
	s_waitcnt lgkmcnt(0)
	v_add_f32_e32 v83, v83, v88
	ds_bpermute_b32 v88, v78, v83
	s_waitcnt lgkmcnt(0)
	v_add_f32_e32 v83, v83, v88
	ds_bpermute_b32 v88, v79, v83
	s_waitcnt lgkmcnt(0)
	v_add_f32_e32 v83, v83, v88
	ds_bpermute_b32 v88, v80, v83
	s_waitcnt lgkmcnt(0)
	v_add_f32_e32 v83, v83, v88
	ds_bpermute_b32 v88, v81, v83
	s_waitcnt lgkmcnt(0)
	v_add_f32_e32 v83, v83, v88
	v_fmamk_f32 v83, v83, 0x3a800000, v82
	v_mul_f32_e32 v88, 0x4b800000, v83
	v_cmp_gt_f32_e64 s[8:9], s11, v83
	s_nop 1
	v_cndmask_b32_e64 v83, v83, v88, s[8:9]
	v_rsq_f32_e32 v83, v83
	s_nop 0
	v_mul_f32_e32 v88, 0x45800000, v83
	v_cndmask_b32_e64 v88, v83, v88, s[8:9]
	v_pk_mul_f32 v[60:61], v[60:61], v[88:89] op_sel_hi:[1,0]
	v_pk_mul_f32 v[62:63], v[62:63], v[88:89] op_sel_hi:[1,0]
	v_pk_mul_f32 v[58:59], v[58:59], v[88:89] op_sel_hi:[1,0]
	v_pk_mul_f32 v[56:57], v[56:57], v[88:89] op_sel_hi:[1,0]
	v_pk_mul_f32 v[62:63], v[234:235], v[62:63]
	v_pk_mul_f32 v[60:61], v[232:233], v[60:61]
	global_store_dwordx4 v[74:75], v[60:63], off nt
	v_pk_mul_f32 v[54:55], v[54:55], v[88:89] op_sel_hi:[1,0]
	v_pk_mul_f32 v[52:53], v[52:53], v[88:89] op_sel_hi:[1,0]
	v_pk_mul_f32 v[50:51], v[50:51], v[88:89] op_sel_hi:[1,0]
	v_pk_mul_f32 v[48:49], v[48:49], v[88:89] op_sel_hi:[1,0]
	v_pk_mul_f32 v[56:57], v[236:237], v[56:57]
	v_pk_mul_f32 v[58:59], v[238:239], v[58:59]
	global_store_dwordx4 v[74:75], v[56:59], off offset:1024 nt
	v_pk_mul_f32 v[52:53], v[240:241], v[52:53]
	v_pk_mul_f32 v[54:55], v[242:243], v[54:55]
	global_store_dwordx4 v[74:75], v[52:55], off offset:2048 nt
	v_pk_mul_f32 v[48:49], v[244:245], v[48:49]
	v_pk_mul_f32 v[50:51], v[246:247], v[50:51]
	global_store_dwordx4 v[74:75], v[48:51], off offset:3072 nt
	s_and_saveexec_b64 s[8:9], s[6:7]
	s_cbranch_execz .LBB0_1988
	v_mov_b32_e32 v54, v41
	v_mov_b32_e32 v55, v45
	v_mov_b32_e32 v52, v40
	v_mov_b32_e32 v53, v44
	v_mov_b32_e32 v62, v33
	v_mov_b32_e32 v63, v37
	v_pk_mul_f32 v[54:55], v[54:55], v[54:55]
	v_mov_b32_e32 v56, v42
	v_mov_b32_e32 v57, v46
	v_mov_b32_e32 v60, v32
	v_mov_b32_e32 v61, v36
	v_pk_mul_f32 v[62:63], v[62:63], v[62:63]
	v_pk_fma_f32 v[52:53], v[52:53], v[52:53], v[54:55]
	v_mov_b32_e32 v58, v43
	v_mov_b32_e32 v59, v47
	v_mov_b32_e32 v74, v34
	v_mov_b32_e32 v75, v38
	v_pk_fma_f32 v[54:55], v[60:61], v[60:61], v[62:63]
	v_pk_fma_f32 v[52:53], v[56:57], v[56:57], v[52:53]
	v_mov_b32_e32 v84, v35
	v_mov_b32_e32 v85, v39
	v_pk_fma_f32 v[54:55], v[74:75], v[74:75], v[54:55]
	v_pk_fma_f32 v[52:53], v[58:59], v[58:59], v[52:53]
	v_pk_fma_f32 v[54:55], v[84:85], v[84:85], v[54:55]
	v_add_f32_e32 v52, v52, v53
	v_add_f32_e32 v52, v55, v52
	v_add_f32_e32 v52, v54, v52
	ds_bpermute_b32 v53, v76, v52
	s_waitcnt lgkmcnt(0)
	v_add_f32_e32 v52, v52, v53
	ds_bpermute_b32 v53, v77, v52
	s_waitcnt lgkmcnt(0)
	v_add_f32_e32 v52, v52, v53
	ds_bpermute_b32 v53, v78, v52
	s_waitcnt lgkmcnt(0)
	v_add_f32_e32 v52, v52, v53
	ds_bpermute_b32 v53, v79, v52
	s_waitcnt lgkmcnt(0)
	v_add_f32_e32 v52, v52, v53
	ds_bpermute_b32 v53, v80, v52
	s_waitcnt lgkmcnt(0)
	v_add_f32_e32 v52, v52, v53
	ds_bpermute_b32 v53, v81, v52
	s_waitcnt lgkmcnt(0)
	v_add_f32_e32 v52, v52, v53
	v_fmamk_f32 v52, v52, 0x3a800000, v82
	v_mul_f32_e32 v53, 0x4b800000, v52
	v_cmp_gt_f32_e64 s[6:7], s11, v52
	s_nop 1
	v_cndmask_b32_e64 v52, v52, v53, s[6:7]
	v_rsq_f32_e32 v54, v52
	v_lshlrev_b64 v[52:53], 12, v[68:69]
	v_lshl_add_u64 v[52:53], v[64:65], 0, v[52:53]
	v_mul_f32_e32 v55, 0x45800000, v54
	v_cndmask_b32_e64 v54, v54, v55, s[6:7]
	v_pk_mul_f32 v[56:57], v[44:45], v[54:55] op_sel_hi:[1,0]
	v_pk_mul_f32 v[58:59], v[46:47], v[54:55] op_sel_hi:[1,0]
	v_pk_mul_f32 v[48:49], v[232:233], v[56:57]
	v_pk_mul_f32 v[50:51], v[234:235], v[58:59]
	global_store_dwordx4 v[52:53], v[48:51], off nt
	v_pk_mul_f32 v[56:57], v[42:43], v[54:55] op_sel_hi:[1,0]
	v_pk_mul_f32 v[58:59], v[40:41], v[54:55] op_sel_hi:[1,0]
	v_pk_mul_f32 v[50:51], v[238:239], v[56:57]
	v_pk_mul_f32 v[48:49], v[236:237], v[58:59]
	global_store_dwordx4 v[52:53], v[48:51], off offset:1024 nt
	v_pk_mul_f32 v[56:57], v[38:39], v[54:55] op_sel_hi:[1,0]
	v_pk_mul_f32 v[58:59], v[36:37], v[54:55] op_sel_hi:[1,0]
	v_pk_mul_f32 v[50:51], v[242:243], v[56:57]
	v_pk_mul_f32 v[48:49], v[240:241], v[58:59]
	global_store_dwordx4 v[52:53], v[48:51], off offset:2048 nt
	v_pk_mul_f32 v[56:57], v[34:35], v[54:55] op_sel_hi:[1,0]
	v_pk_mul_f32 v[54:55], v[32:33], v[54:55] op_sel_hi:[1,0]
	v_pk_mul_f32 v[50:51], v[246:247], v[56:57]
	v_pk_mul_f32 v[48:49], v[244:245], v[54:55]
	global_store_dwordx4 v[52:53], v[48:51], off offset:3072 nt
	s_or_b64 exec, exec, s[8:9]
	s_and_saveexec_b64 s[6:7], s[4:5]
	s_cbranch_execnz .LBB0_1989

; __device__ __forceinline__ void final_phase(const Args& a, int wv, int row_lo, int row_hi, int bidx, int nblk) {
;     ...
;         for (int j = 0; j < 4; ++j) {
;             const int row = rb + j * nw;
;             if (row < MT) {
;                 float* x = a.out + (size_t)row * DM;
;                 float ss = 0.f;
; #pragma unroll
;                 for (int i = 0; i < 4; ++i) ss += v[j][i][0] * v[j][i][0] + v[j][i][1] * v[j][i][1] + v[j][i][2] * v[j][i][2] + v[j][i][3] * v[j][i][3];
;                 ss = wave_sum(ss);
;                 const float rstd = rsqrtf(ss * (1.f / 1024.f) + EPS);
; #pragma unroll
;                 for (int i = 0; i < 4; ++i) { const int c = i * 256 + lane * 4; const f32x4 g4 = *(const f32x4*)(g + c); __builtin_nontemporal_store(v[j][i] * rstd * g4, (f32x4*)(x + c)); }
;             }
.LBB0_1989:
	v_mov_b32_e32 v54, v25
	v_mov_b32_e32 v55, v29
	v_mov_b32_e32 v52, v24
	v_mov_b32_e32 v53, v28
	v_mov_b32_e32 v62, v17
	v_mov_b32_e32 v63, v21
	v_pk_mul_f32 v[54:55], v[54:55], v[54:55]
	v_mov_b32_e32 v56, v26
	v_mov_b32_e32 v57, v30
	v_mov_b32_e32 v60, v16
	v_mov_b32_e32 v61, v20
	v_pk_mul_f32 v[62:63], v[62:63], v[62:63]
	v_pk_fma_f32 v[52:53], v[52:53], v[52:53], v[54:55]
	v_mov_b32_e32 v58, v27
	v_mov_b32_e32 v59, v31
	v_mov_b32_e32 v74, v18
	v_mov_b32_e32 v75, v22
	v_pk_fma_f32 v[54:55], v[60:61], v[60:61], v[62:63]
	v_pk_fma_f32 v[52:53], v[56:57], v[56:57], v[52:53]
	v_mov_b32_e32 v84, v19
	v_mov_b32_e32 v85, v23
	v_pk_fma_f32 v[54:55], v[74:75], v[74:75], v[54:55]
	v_pk_fma_f32 v[52:53], v[58:59], v[58:59], v[52:53]
	v_pk_fma_f32 v[54:55], v[84:85], v[84:85], v[54:55]
	v_add_f32_e32 v52, v52, v53
	v_add_f32_e32 v52, v55, v52
	v_add_f32_e32 v52, v54, v52
	ds_bpermute_b32 v53, v76, v52
	s_waitcnt lgkmcnt(0)
	v_add_f32_e32 v52, v52, v53
	ds_bpermute_b32 v53, v77, v52
	s_waitcnt lgkmcnt(0)
	v_add_f32_e32 v52, v52, v53
	ds_bpermute_b32 v53, v78, v52
	s_waitcnt lgkmcnt(0)
	v_add_f32_e32 v52, v52, v53
	ds_bpermute_b32 v53, v79, v52
	s_waitcnt lgkmcnt(0)
	v_add_f32_e32 v52, v52, v53
	ds_bpermute_b32 v53, v80, v52
	s_waitcnt lgkmcnt(0)
	v_add_f32_e32 v52, v52, v53
	ds_bpermute_b32 v53, v81, v52
	s_waitcnt lgkmcnt(0)
	v_add_f32_e32 v52, v52, v53
	v_fmamk_f32 v52, v52, 0x3a800000, v82
	v_mul_f32_e32 v53, 0x4b800000, v52
	v_cmp_gt_f32_e64 s[4:5], s11, v52
	s_nop 1
	v_cndmask_b32_e64 v52, v52, v53, s[4:5]
	v_rsq_f32_e32 v54, v52
	v_lshlrev_b64 v[52:53], 12, v[72:73]
	v_lshl_add_u64 v[52:53], v[64:65], 0, v[52:53]
	v_mul_f32_e32 v55, 0x45800000, v54
	v_cndmask_b32_e64 v54, v54, v55, s[4:5]
	v_pk_mul_f32 v[56:57], v[28:29], v[54:55] op_sel_hi:[1,0]
	v_pk_mul_f32 v[58:59], v[30:31], v[54:55] op_sel_hi:[1,0]
	v_pk_mul_f32 v[48:49], v[232:233], v[56:57]
	v_pk_mul_f32 v[50:51], v[234:235], v[58:59]
	global_store_dwordx4 v[52:53], v[48:51], off nt
	v_pk_mul_f32 v[56:57], v[26:27], v[54:55] op_sel_hi:[1,0]
	v_pk_mul_f32 v[58:59], v[24:25], v[54:55] op_sel_hi:[1,0]
	v_pk_mul_f32 v[50:51], v[238:239], v[56:57]
	v_pk_mul_f32 v[48:49], v[236:237], v[58:59]
	global_store_dwordx4 v[52:53], v[48:51], off offset:1024 nt
	v_pk_mul_f32 v[56:57], v[22:23], v[54:55] op_sel_hi:[1,0]
	v_pk_mul_f32 v[58:59], v[20:21], v[54:55] op_sel_hi:[1,0]
	v_pk_mul_f32 v[50:51], v[242:243], v[56:57]
	v_pk_mul_f32 v[48:49], v[240:241], v[58:59]
	global_store_dwordx4 v[52:53], v[48:51], off offset:2048 nt
	v_pk_mul_f32 v[56:57], v[18:19], v[54:55] op_sel_hi:[1,0]
	v_pk_mul_f32 v[54:55], v[16:17], v[54:55] op_sel_hi:[1,0]
	v_pk_mul_f32 v[50:51], v[246:247], v[56:57]
	v_pk_mul_f32 v[48:49], v[244:245], v[54:55]
	global_store_dwordx4 v[52:53], v[48:51], off offset:3072 nt
	s_or_b64 exec, exec, s[6:7]
	s_and_saveexec_b64 s[4:5], vcc
	s_cbranch_execz .LBB0_1978
.LBB0_1990:
	v_mov_b32_e32 v54, v9
	v_mov_b32_e32 v55, v13
	v_mov_b32_e32 v52, v8
	v_mov_b32_e32 v53, v12
	v_mov_b32_e32 v62, v1
	v_mov_b32_e32 v63, v5
	v_pk_mul_f32 v[54:55], v[54:55], v[54:55]
	v_mov_b32_e32 v56, v10
	v_mov_b32_e32 v57, v14
	v_mov_b32_e32 v60, v0
	v_mov_b32_e32 v61, v4
	v_pk_mul_f32 v[62:63], v[62:63], v[62:63]
	v_pk_fma_f32 v[52:53], v[52:53], v[52:53], v[54:55]
	v_mov_b32_e32 v58, v11
	v_mov_b32_e32 v59, v15
	v_mov_b32_e32 v72, v2
	v_mov_b32_e32 v73, v6
	v_pk_fma_f32 v[54:55], v[60:61], v[60:61], v[62:63]
	v_pk_fma_f32 v[52:53], v[56:57], v[56:57], v[52:53]
	v_mov_b32_e32 v74, v3
	v_mov_b32_e32 v75, v7
	v_pk_fma_f32 v[54:55], v[72:73], v[72:73], v[54:55]
	v_pk_fma_f32 v[52:53], v[58:59], v[58:59], v[52:53]
	v_pk_fma_f32 v[54:55], v[74:75], v[74:75], v[54:55]
	v_add_f32_e32 v52, v52, v53
	v_add_f32_e32 v52, v55, v52
	v_add_f32_e32 v52, v54, v52
	ds_bpermute_b32 v53, v76, v52
	s_waitcnt lgkmcnt(0)
	v_add_f32_e32 v52, v52, v53
	ds_bpermute_b32 v53, v77, v52
	s_waitcnt lgkmcnt(0)
	v_add_f32_e32 v52, v52, v53
	ds_bpermute_b32 v53, v78, v52
	s_waitcnt lgkmcnt(0)
	v_add_f32_e32 v52, v52, v53
	ds_bpermute_b32 v53, v79, v52
	s_waitcnt lgkmcnt(0)
	v_add_f32_e32 v52, v52, v53
	ds_bpermute_b32 v53, v80, v52
	s_waitcnt lgkmcnt(0)
	v_add_f32_e32 v52, v52, v53
	ds_bpermute_b32 v53, v81, v52
	s_waitcnt lgkmcnt(0)
	v_add_f32_e32 v52, v52, v53
	v_fmamk_f32 v52, v52, 0x3a800000, v82
	v_mul_f32_e32 v53, 0x4b800000, v52
	v_cmp_gt_f32_e32 vcc, s11, v52
	s_nop 1
	v_cndmask_b32_e32 v52, v52, v53, vcc
	v_rsq_f32_e32 v54, v52
	v_lshlrev_b64 v[52:53], 12, v[70:71]
	v_lshl_add_u64 v[52:53], v[64:65], 0, v[52:53]
	v_mul_f32_e32 v55, 0x45800000, v54
	v_cndmask_b32_e32 v54, v54, v55, vcc
	v_pk_mul_f32 v[56:57], v[12:13], v[54:55] op_sel_hi:[1,0]
	v_pk_mul_f32 v[58:59], v[14:15], v[54:55] op_sel_hi:[1,0]
	v_pk_mul_f32 v[48:49], v[232:233], v[56:57]
	v_pk_mul_f32 v[50:51], v[234:235], v[58:59]
	global_store_dwordx4 v[52:53], v[48:51], off nt
	v_pk_mul_f32 v[56:57], v[10:11], v[54:55] op_sel_hi:[1,0]
	v_pk_mul_f32 v[58:59], v[8:9], v[54:55] op_sel_hi:[1,0]
	v_pk_mul_f32 v[50:51], v[238:239], v[56:57]
	v_pk_mul_f32 v[48:49], v[236:237], v[58:59]
	global_store_dwordx4 v[52:53], v[48:51], off offset:1024 nt
	v_pk_mul_f32 v[56:57], v[6:7], v[54:55] op_sel_hi:[1,0]
	v_pk_mul_f32 v[58:59], v[4:5], v[54:55] op_sel_hi:[1,0]
	v_pk_mul_f32 v[50:51], v[242:243], v[56:57]
	v_pk_mul_f32 v[48:49], v[240:241], v[58:59]
	global_store_dwordx4 v[52:53], v[48:51], off offset:2048 nt
	v_pk_mul_f32 v[56:57], v[2:3], v[54:55] op_sel_hi:[1,0]
	v_pk_mul_f32 v[54:55], v[0:1], v[54:55] op_sel_hi:[1,0]
	v_pk_mul_f32 v[50:51], v[246:247], v[56:57]
	v_pk_mul_f32 v[48:49], v[244:245], v[54:55]
	global_store_dwordx4 v[52:53], v[48:51], off offset:3072 nt
	s_branch .LBB0_1978

; __device__ __forceinline__ int otid(int wv) { (void)wv; int t = threadIdx.x; asm volatile("" : "+v"(t)); return t; }
; __device__ __forceinline__ void final_phase(const Args& a, int wv, int row_lo, int row_hi, int bidx, int nblk) {
;     const int tid_ = otid(wv); const int lane = tid_ & 63, wid = tid_ >> 6;
;     const float* g = a.in[32];
;     const int nw = nblk * 8;
;     const int MT = row_hi;
;     for (int rb = row_lo + bidx * 8 + wid; rb < MT; rb += nw * 4) {
;         f32x4 v[4][4];
; #pragma unroll
;         for (int j = 0; j < 4; ++j) {
;             const int row = rb + j * nw;
;             if (row < MT) {
;                 const float* x = a.out + (size_t)row * DM;
; #pragma unroll
;                 for (int i = 0; i < 4; ++i) v[j][i] = *(const f32x4*)(x + i * 256 + lane * 4);
.LBB0_1992:
	s_andn2_b64 vcc, exec, s[0:1]
	s_cbranch_vccnz .LBB0_2009
	s_waitcnt lgkmcnt(0)
	v_mov_b32_e32 v1, v215
	s_mov_b32 s0, 0x10000
	v_ashrrev_i32_e32 v0, 6, v1
	v_add_u32_e32 v86, s22, v0
	v_cmp_gt_i32_e32 vcc, s0, v86
	s_and_saveexec_b64 s[0:1], vcc
	s_cbranch_execz .LBB0_2008
	v_and_b32_e32 v2, 64, v248
	v_add_u32_e32 v2, 64, v2
	v_xor_b32_e32 v3, 32, v248
	v_cmp_lt_i32_e32 vcc, v3, v2
	v_mov_b32_e32 v65, 0
	s_mov_b64 s[2:3], 0
	v_cndmask_b32_e32 v3, v248, v3, vcc
	v_lshlrev_b32_e32 v84, 2, v3
	v_xor_b32_e32 v3, 16, v248
	v_cmp_lt_i32_e32 vcc, v3, v2
	v_mov_b32_e32 v91, 0x358637bd
	s_mov_b64 s[10:11], 0x1f00000
	v_cndmask_b32_e32 v3, v248, v3, vcc
	v_lshlrev_b32_e32 v85, 2, v3
	v_xor_b32_e32 v3, 8, v248
	v_cmp_lt_i32_e32 vcc, v3, v2
	s_mov_b32 s17, 0xe0ff
	s_nop 0
	v_cndmask_b32_e32 v3, v248, v3, vcc
	v_lshlrev_b32_e32 v87, 2, v3
	v_xor_b32_e32 v3, 4, v248
	v_cmp_lt_i32_e32 vcc, v3, v2
	s_nop 1
	v_cndmask_b32_e32 v3, v248, v3, vcc
	v_lshlrev_b32_e32 v88, 2, v3
	v_xor_b32_e32 v3, 2, v248
	v_cmp_lt_i32_e32 vcc, v3, v2
	s_nop 1
	v_cndmask_b32_e32 v3, v248, v3, vcc
	v_lshlrev_b32_e32 v89, 2, v3
	v_xor_b32_e32 v3, 1, v248
	v_cmp_lt_i32_e32 vcc, v3, v2
	s_nop 1
	v_cndmask_b32_e32 v2, v248, v3, vcc
	v_lshlrev_b32_e32 v90, 2, v2
	v_lshlrev_b32_e32 v2, 4, v1
	v_and_b32_e32 v64, 0x3f0, v2
	v_and_b32_e32 v1, 63, v1
	v_lshl_add_u64 v[66:67], s[12:13], 0, v[64:65]
	global_load_dwordx4 v[232:235], v[66:67], off
	global_load_dwordx4 v[236:239], v[66:67], off offset:1024
	global_load_dwordx4 v[240:243], v[66:67], off offset:2048
	global_load_dwordx4 v[244:247], v[66:67], off offset:3072
	v_lshlrev_b32_e32 v64, 4, v1
	v_ashrrev_i32_e32 v1, 31, v0
	v_lshl_add_u64 v[0:1], v[0:1], 0, s[22:23]
	v_lshlrev_b64 v[0:1], 12, v[0:1]
	v_lshl_add_u64 v[68:69], s[14:15], 0, v[0:1]
	v_add_u32_e32 v0, 0x1740, v86
	v_ashrrev_i32_e32 v1, 31, v0
	v_lshlrev_b64 v[0:1], 12, v[0:1]
	v_lshl_add_u64 v[70:71], s[14:15], 0, v[0:1]
	v_add_u32_e32 v0, 0x7c0, v86
	v_ashrrev_i32_e32 v1, 31, v0
	v_lshlrev_b64 v[0:1], 12, v[0:1]
	v_lshl_add_u64 v[72:73], s[14:15], 0, v[0:1]
	v_add_u32_e32 v0, 0xf80, v86
	v_ashrrev_i32_e32 v1, 31, v0
	v_lshlrev_b64 v[0:1], 12, v[0:1]
	v_lshl_add_u64 v[74:75], s[14:15], 0, v[0:1]
	s_mov_b32 s12, 0xf840
	s_mov_b32 s13, 0xf080
	s_mov_b32 s14, 0xe8c0
	s_mov_b32 s15, 0x800000
	s_branch .LBB0_1996

; __device__ __forceinline__ void final_phase(const Args& a, int wv, int row_lo, int row_hi, int bidx, int nblk) {
;     ...
;         for (int j = 0; j < 4; ++j) {
;             const int row = rb + j * nw;
;             if (row < MT) {
;                 float* x = a.out + (size_t)row * DM;
;                 float ss = 0.f;
; #pragma unroll
;                 for (int i = 0; i < 4; ++i) ss += v[j][i][0] * v[j][i][0] + v[j][i][1] * v[j][i][1] + v[j][i][2] * v[j][i][2] + v[j][i][3] * v[j][i][3];
;                 ss = wave_sum(ss);
;                 const float rstd = rsqrtf(ss * (1.f / 1024.f) + EPS);
; #pragma unroll
;                 for (int i = 0; i < 4; ++i) { const int c = i * 256 + lane * 4; const f32x4 g4 = *(const f32x4*)(g + c); __builtin_nontemporal_store(v[j][i] * rstd * g4, (f32x4*)(x + c)); }
;             }
.LBB0_2002:
	s_or_b64 exec, exec, s[8:9]
	s_waitcnt vmcnt(0)
	v_mov_b32_e32 v98, v61
	v_mov_b32_e32 v99, v57
	v_mov_b32_e32 v96, v60
	v_mov_b32_e32 v97, v56
	v_mov_b32_e32 v106, v53
	v_mov_b32_e32 v107, v49
	v_pk_mul_f32 v[98:99], v[98:99], v[98:99]
	v_mov_b32_e32 v100, v62
	v_mov_b32_e32 v101, v58
	v_mov_b32_e32 v104, v52
	v_mov_b32_e32 v105, v48
	v_pk_mul_f32 v[106:107], v[106:107], v[106:107]
	v_pk_fma_f32 v[96:97], v[96:97], v[96:97], v[98:99]
	v_mov_b32_e32 v102, v63
	v_mov_b32_e32 v103, v59
	v_mov_b32_e32 v108, v54
	v_mov_b32_e32 v109, v50
	v_pk_fma_f32 v[98:99], v[104:105], v[104:105], v[106:107]
	v_pk_fma_f32 v[96:97], v[100:101], v[100:101], v[96:97]
	v_mov_b32_e32 v110, v55
	v_mov_b32_e32 v111, v51
	v_pk_fma_f32 v[98:99], v[108:109], v[108:109], v[98:99]
	v_pk_fma_f32 v[96:97], v[102:103], v[102:103], v[96:97]
	v_pk_fma_f32 v[98:99], v[110:111], v[110:111], v[98:99]
	v_add_f32_e32 v96, v96, v97
	v_add_f32_e32 v96, v96, v98
	v_add_f32_e32 v96, v96, v99
	ds_bpermute_b32 v97, v84, v96
	s_waitcnt lgkmcnt(0)
	v_add_f32_e32 v96, v96, v97
	ds_bpermute_b32 v97, v85, v96
	s_waitcnt lgkmcnt(0)
	v_add_f32_e32 v96, v96, v97
	ds_bpermute_b32 v97, v87, v96
	s_waitcnt lgkmcnt(0)
	v_add_f32_e32 v96, v96, v97
	ds_bpermute_b32 v97, v88, v96
	s_waitcnt lgkmcnt(0)
	v_add_f32_e32 v96, v96, v97
	ds_bpermute_b32 v97, v89, v96
	s_waitcnt lgkmcnt(0)
	v_add_f32_e32 v96, v96, v97
	ds_bpermute_b32 v97, v90, v96
	s_waitcnt lgkmcnt(0)
	v_add_f32_e32 v96, v96, v97
	v_fmamk_f32 v96, v96, 0x3a800000, v91
	v_mul_f32_e32 v97, 0x4b800000, v96
	v_cmp_gt_f32_e64 s[8:9], s15, v96
	s_nop 1
	v_cndmask_b32_e64 v96, v96, v97, s[8:9]
	v_rsq_f32_e32 v96, v96
	s_nop 0
	v_mul_f32_e32 v97, 0x45800000, v96
	v_cndmask_b32_e64 v96, v96, v97, s[8:9]
	v_pk_mul_f32 v[60:61], v[60:61], v[96:97] op_sel_hi:[1,0]
	v_pk_mul_f32 v[62:63], v[62:63], v[96:97] op_sel_hi:[1,0]
	v_pk_mul_f32 v[58:59], v[58:59], v[96:97] op_sel_hi:[1,0]
	v_pk_mul_f32 v[56:57], v[56:57], v[96:97] op_sel_hi:[1,0]
	v_pk_mul_f32 v[62:63], v[234:235], v[62:63]
	v_pk_mul_f32 v[60:61], v[232:233], v[60:61]
	global_store_dwordx4 v[82:83], v[60:63], off nt
	v_pk_mul_f32 v[54:55], v[54:55], v[96:97] op_sel_hi:[1,0]
	v_pk_mul_f32 v[52:53], v[52:53], v[96:97] op_sel_hi:[1,0]
	v_pk_mul_f32 v[50:51], v[50:51], v[96:97] op_sel_hi:[1,0]
	v_pk_mul_f32 v[48:49], v[48:49], v[96:97] op_sel_hi:[1,0]
	v_pk_mul_f32 v[56:57], v[236:237], v[56:57]
	v_pk_mul_f32 v[58:59], v[238:239], v[58:59]
	global_store_dwordx4 v[82:83], v[56:59], off offset:1024 nt
	v_pk_mul_f32 v[52:53], v[240:241], v[52:53]
	v_pk_mul_f32 v[54:55], v[242:243], v[54:55]
	global_store_dwordx4 v[82:83], v[52:55], off offset:2048 nt
	v_pk_mul_f32 v[48:49], v[244:245], v[48:49]
	v_pk_mul_f32 v[50:51], v[246:247], v[50:51]
	global_store_dwordx4 v[82:83], v[48:51], off offset:3072 nt
	s_and_saveexec_b64 s[8:9], s[6:7]
	s_cbranch_execz .LBB0_2005
	v_mov_b32_e32 v54, v41
	v_mov_b32_e32 v55, v45
	v_mov_b32_e32 v52, v40
	v_mov_b32_e32 v53, v44
	v_mov_b32_e32 v62, v33
	v_mov_b32_e32 v63, v37
	v_pk_mul_f32 v[54:55], v[54:55], v[54:55]
	v_mov_b32_e32 v56, v42
	v_mov_b32_e32 v57, v46
	v_mov_b32_e32 v60, v32
	v_mov_b32_e32 v61, v36
	v_pk_mul_f32 v[62:63], v[62:63], v[62:63]
	v_pk_fma_f32 v[52:53], v[52:53], v[52:53], v[54:55]
	v_mov_b32_e32 v58, v43
	v_mov_b32_e32 v59, v47
	v_mov_b32_e32 v82, v34
	v_mov_b32_e32 v83, v38
	v_pk_fma_f32 v[54:55], v[60:61], v[60:61], v[62:63]
	v_pk_fma_f32 v[52:53], v[56:57], v[56:57], v[52:53]
	v_mov_b32_e32 v92, v35
	v_mov_b32_e32 v93, v39
	v_pk_fma_f32 v[54:55], v[82:83], v[82:83], v[54:55]
	v_pk_fma_f32 v[52:53], v[58:59], v[58:59], v[52:53]
	v_pk_fma_f32 v[54:55], v[92:93], v[92:93], v[54:55]
	v_add_f32_e32 v52, v52, v53
	v_add_f32_e32 v52, v55, v52
	v_add_f32_e32 v52, v54, v52
	ds_bpermute_b32 v53, v84, v52
	s_waitcnt lgkmcnt(0)
	v_add_f32_e32 v52, v52, v53
	ds_bpermute_b32 v53, v85, v52
	s_waitcnt lgkmcnt(0)
	v_add_f32_e32 v52, v52, v53
	ds_bpermute_b32 v53, v87, v52
	s_waitcnt lgkmcnt(0)
	v_add_f32_e32 v52, v52, v53
	ds_bpermute_b32 v53, v88, v52
	s_waitcnt lgkmcnt(0)
	v_add_f32_e32 v52, v52, v53
	ds_bpermute_b32 v53, v89, v52
	s_waitcnt lgkmcnt(0)
	v_add_f32_e32 v52, v52, v53
	ds_bpermute_b32 v53, v90, v52
	s_waitcnt lgkmcnt(0)
	v_add_f32_e32 v52, v52, v53
	v_fmamk_f32 v52, v52, 0x3a800000, v91
	v_mul_f32_e32 v53, 0x4b800000, v52
	v_cmp_gt_f32_e64 s[6:7], s15, v52
	s_nop 1
	v_cndmask_b32_e64 v52, v52, v53, s[6:7]
	v_rsq_f32_e32 v52, v52
	s_nop 0
	v_mul_f32_e32 v53, 0x45800000, v52
	v_cndmask_b32_e64 v52, v52, v53, s[6:7]
	v_pk_mul_f32 v[54:55], v[44:45], v[52:53] op_sel_hi:[1,0]
	v_pk_mul_f32 v[56:57], v[46:47], v[52:53] op_sel_hi:[1,0]
	v_pk_mul_f32 v[48:49], v[232:233], v[54:55]
	v_pk_mul_f32 v[50:51], v[234:235], v[56:57]
	global_store_dwordx4 v[80:81], v[48:51], off nt
	v_pk_mul_f32 v[54:55], v[42:43], v[52:53] op_sel_hi:[1,0]
	v_pk_mul_f32 v[56:57], v[40:41], v[52:53] op_sel_hi:[1,0]
	v_pk_mul_f32 v[50:51], v[238:239], v[54:55]
	v_pk_mul_f32 v[48:49], v[236:237], v[56:57]
	global_store_dwordx4 v[80:81], v[48:51], off offset:1024 nt
	v_pk_mul_f32 v[54:55], v[38:39], v[52:53] op_sel_hi:[1,0]
	v_pk_mul_f32 v[56:57], v[36:37], v[52:53] op_sel_hi:[1,0]
	v_pk_mul_f32 v[50:51], v[242:243], v[54:55]
	v_pk_mul_f32 v[48:49], v[240:241], v[56:57]
	global_store_dwordx4 v[80:81], v[48:51], off offset:2048 nt
	v_pk_mul_f32 v[54:55], v[34:35], v[52:53] op_sel_hi:[1,0]
	v_pk_mul_f32 v[52:53], v[32:33], v[52:53] op_sel_hi:[1,0]
	v_pk_mul_f32 v[50:51], v[246:247], v[54:55]
	v_pk_mul_f32 v[48:49], v[244:245], v[52:53]
	global_store_dwordx4 v[80:81], v[48:51], off offset:3072 nt
	s_or_b64 exec, exec, s[8:9]
	s_and_saveexec_b64 s[6:7], s[4:5]
	s_cbranch_execnz .LBB0_2006

; __device__ __forceinline__ void final_phase(const Args& a, int wv, int row_lo, int row_hi, int bidx, int nblk) {
;     ...
;         for (int j = 0; j < 4; ++j) {
;             const int row = rb + j * nw;
;             if (row < MT) {
;                 float* x = a.out + (size_t)row * DM;
;                 float ss = 0.f;
; #pragma unroll
;                 for (int i = 0; i < 4; ++i) ss += v[j][i][0] * v[j][i][0] + v[j][i][1] * v[j][i][1] + v[j][i][2] * v[j][i][2] + v[j][i][3] * v[j][i][3];
;                 ss = wave_sum(ss);
;                 const float rstd = rsqrtf(ss * (1.f / 1024.f) + EPS);
; #pragma unroll
;                 for (int i = 0; i < 4; ++i) { const int c = i * 256 + lane * 4; const f32x4 g4 = *(const f32x4*)(g + c); __builtin_nontemporal_store(v[j][i] * rstd * g4, (f32x4*)(x + c)); }
;             }
.LBB0_2006:
	v_mov_b32_e32 v54, v25
	v_mov_b32_e32 v55, v29
	v_mov_b32_e32 v52, v24
	v_mov_b32_e32 v53, v28
	v_mov_b32_e32 v62, v17
	v_mov_b32_e32 v63, v21
	v_pk_mul_f32 v[54:55], v[54:55], v[54:55]
	v_mov_b32_e32 v56, v26
	v_mov_b32_e32 v57, v30
	v_mov_b32_e32 v60, v16
	v_mov_b32_e32 v61, v20
	v_pk_mul_f32 v[62:63], v[62:63], v[62:63]
	v_pk_fma_f32 v[52:53], v[52:53], v[52:53], v[54:55]
	v_mov_b32_e32 v58, v27
	v_mov_b32_e32 v59, v31
	v_mov_b32_e32 v80, v18
	v_mov_b32_e32 v81, v22
	v_pk_fma_f32 v[54:55], v[60:61], v[60:61], v[62:63]
	v_pk_fma_f32 v[52:53], v[56:57], v[56:57], v[52:53]
	v_mov_b32_e32 v82, v19
	v_mov_b32_e32 v83, v23
	v_pk_fma_f32 v[54:55], v[80:81], v[80:81], v[54:55]
	v_pk_fma_f32 v[52:53], v[58:59], v[58:59], v[52:53]
	v_pk_fma_f32 v[54:55], v[82:83], v[82:83], v[54:55]
	v_add_f32_e32 v52, v52, v53
	v_add_f32_e32 v52, v55, v52
	v_add_f32_e32 v52, v54, v52
	ds_bpermute_b32 v53, v84, v52
	s_waitcnt lgkmcnt(0)
	v_add_f32_e32 v52, v52, v53
	ds_bpermute_b32 v53, v85, v52
	s_waitcnt lgkmcnt(0)
	v_add_f32_e32 v52, v52, v53
	ds_bpermute_b32 v53, v87, v52
	s_waitcnt lgkmcnt(0)
	v_add_f32_e32 v52, v52, v53
	ds_bpermute_b32 v53, v88, v52
	s_waitcnt lgkmcnt(0)
	v_add_f32_e32 v52, v52, v53
	ds_bpermute_b32 v53, v89, v52
	s_waitcnt lgkmcnt(0)
	v_add_f32_e32 v52, v52, v53
	ds_bpermute_b32 v53, v90, v52
	s_waitcnt lgkmcnt(0)
	v_add_f32_e32 v52, v52, v53
	v_fmamk_f32 v52, v52, 0x3a800000, v91
	v_mul_f32_e32 v53, 0x4b800000, v52
	v_cmp_gt_f32_e64 s[4:5], s15, v52
	s_nop 1
	v_cndmask_b32_e64 v52, v52, v53, s[4:5]
	v_rsq_f32_e32 v52, v52
	s_nop 0
	v_mul_f32_e32 v53, 0x45800000, v52
	v_cndmask_b32_e64 v52, v52, v53, s[4:5]
	v_pk_mul_f32 v[54:55], v[28:29], v[52:53] op_sel_hi:[1,0]
	v_pk_mul_f32 v[56:57], v[30:31], v[52:53] op_sel_hi:[1,0]
	v_pk_mul_f32 v[48:49], v[232:233], v[54:55]
	v_pk_mul_f32 v[50:51], v[234:235], v[56:57]
	global_store_dwordx4 v[78:79], v[48:51], off nt
	v_pk_mul_f32 v[54:55], v[26:27], v[52:53] op_sel_hi:[1,0]
	v_pk_mul_f32 v[56:57], v[24:25], v[52:53] op_sel_hi:[1,0]
	v_pk_mul_f32 v[50:51], v[238:239], v[54:55]
	v_pk_mul_f32 v[48:49], v[236:237], v[56:57]
	global_store_dwordx4 v[78:79], v[48:51], off offset:1024 nt
	v_pk_mul_f32 v[54:55], v[22:23], v[52:53] op_sel_hi:[1,0]
	v_pk_mul_f32 v[56:57], v[20:21], v[52:53] op_sel_hi:[1,0]
	v_pk_mul_f32 v[50:51], v[242:243], v[54:55]
	v_pk_mul_f32 v[48:49], v[240:241], v[56:57]
	global_store_dwordx4 v[78:79], v[48:51], off offset:2048 nt
	v_pk_mul_f32 v[54:55], v[18:19], v[52:53] op_sel_hi:[1,0]
	v_pk_mul_f32 v[52:53], v[16:17], v[52:53] op_sel_hi:[1,0]
	v_pk_mul_f32 v[50:51], v[246:247], v[54:55]
	v_pk_mul_f32 v[48:49], v[244:245], v[52:53]
	global_store_dwordx4 v[78:79], v[48:51], off offset:3072 nt
	s_or_b64 exec, exec, s[6:7]
	s_and_saveexec_b64 s[4:5], vcc
	s_cbranch_execz .LBB0_1995
.LBB0_2007:
	v_mov_b32_e32 v54, v9
	v_mov_b32_e32 v55, v13
	v_mov_b32_e32 v52, v8
	v_mov_b32_e32 v53, v12
	v_mov_b32_e32 v62, v1
	v_mov_b32_e32 v63, v5
	v_pk_mul_f32 v[54:55], v[54:55], v[54:55]
	v_mov_b32_e32 v56, v10
	v_mov_b32_e32 v57, v14
	v_mov_b32_e32 v60, v0
	v_mov_b32_e32 v61, v4
	v_pk_mul_f32 v[62:63], v[62:63], v[62:63]
	v_pk_fma_f32 v[52:53], v[52:53], v[52:53], v[54:55]
	v_mov_b32_e32 v58, v11
	v_mov_b32_e32 v59, v15
	v_mov_b32_e32 v78, v2
	v_mov_b32_e32 v79, v6
	v_pk_fma_f32 v[54:55], v[60:61], v[60:61], v[62:63]
	v_pk_fma_f32 v[52:53], v[56:57], v[56:57], v[52:53]
	v_mov_b32_e32 v80, v3
	v_mov_b32_e32 v81, v7
	v_pk_fma_f32 v[54:55], v[78:79], v[78:79], v[54:55]
	v_pk_fma_f32 v[52:53], v[58:59], v[58:59], v[52:53]
	v_pk_fma_f32 v[54:55], v[80:81], v[80:81], v[54:55]
	v_add_f32_e32 v52, v52, v53
	v_add_f32_e32 v52, v55, v52
	v_add_f32_e32 v52, v54, v52
	ds_bpermute_b32 v53, v84, v52
	s_waitcnt lgkmcnt(0)
	v_add_f32_e32 v52, v52, v53
	ds_bpermute_b32 v53, v85, v52
	s_waitcnt lgkmcnt(0)
	v_add_f32_e32 v52, v52, v53
	ds_bpermute_b32 v53, v87, v52
	s_waitcnt lgkmcnt(0)
	v_add_f32_e32 v52, v52, v53
	ds_bpermute_b32 v53, v88, v52
	s_waitcnt lgkmcnt(0)
	v_add_f32_e32 v52, v52, v53
	ds_bpermute_b32 v53, v89, v52
	s_waitcnt lgkmcnt(0)
	v_add_f32_e32 v52, v52, v53
	ds_bpermute_b32 v53, v90, v52
	s_waitcnt lgkmcnt(0)
	v_add_f32_e32 v52, v52, v53
	v_fmamk_f32 v52, v52, 0x3a800000, v91
	v_mul_f32_e32 v53, 0x4b800000, v52
	v_cmp_gt_f32_e32 vcc, s15, v52
	s_nop 1
	v_cndmask_b32_e32 v52, v52, v53, vcc
	v_rsq_f32_e32 v52, v52
	s_nop 0
	v_mul_f32_e32 v53, 0x45800000, v52
	v_cndmask_b32_e32 v52, v52, v53, vcc
	v_pk_mul_f32 v[54:55], v[12:13], v[52:53] op_sel_hi:[1,0]
	v_pk_mul_f32 v[56:57], v[14:15], v[52:53] op_sel_hi:[1,0]
	v_pk_mul_f32 v[48:49], v[232:233], v[54:55]
	v_pk_mul_f32 v[50:51], v[234:235], v[56:57]
	global_store_dwordx4 v[76:77], v[48:51], off nt
	v_pk_mul_f32 v[54:55], v[10:11], v[52:53] op_sel_hi:[1,0]
	v_pk_mul_f32 v[56:57], v[8:9], v[52:53] op_sel_hi:[1,0]
	v_pk_mul_f32 v[50:51], v[238:239], v[54:55]
	v_pk_mul_f32 v[48:49], v[236:237], v[56:57]
	global_store_dwordx4 v[76:77], v[48:51], off offset:1024 nt
	v_pk_mul_f32 v[54:55], v[6:7], v[52:53] op_sel_hi:[1,0]
	v_pk_mul_f32 v[56:57], v[4:5], v[52:53] op_sel_hi:[1,0]
	v_pk_mul_f32 v[50:51], v[242:243], v[54:55]
	v_pk_mul_f32 v[48:49], v[240:241], v[56:57]
	global_store_dwordx4 v[76:77], v[48:51], off offset:2048 nt
	v_pk_mul_f32 v[54:55], v[2:3], v[52:53] op_sel_hi:[1,0]
	v_pk_mul_f32 v[52:53], v[0:1], v[52:53] op_sel_hi:[1,0]
	v_pk_mul_f32 v[50:51], v[246:247], v[54:55]
	v_pk_mul_f32 v[48:49], v[244:245], v[52:53]
	global_store_dwordx4 v[76:77], v[48:51], off offset:3072 nt
	s_branch .LBB0_1995

; __device__ __forceinline__ int otid(int wv) { (void)wv; int t = threadIdx.x; asm volatile("" : "+v"(t)); return t; }
; __device__ __forceinline__ void wait_count(unsigned* cnt, unsigned need) {
;     ...
;     __builtin_amdgcn_fence(__ATOMIC_ACQUIRE, "agent");
;     asm volatile("s_waitcnt vmcnt(0)" ::: "memory");
; __device__ __forceinline__ void final_phase(const Args& a, int wv, int row_lo, int row_hi, int bidx, int nblk) {
;     const int tid_ = otid(wv); const int lane = tid_ & 63, wid = tid_ >> 6;
;     const float* g = a.in[32];
;     const int nw = nblk * 8;
;     const int MT = row_hi;
;     for (int rb = row_lo + bidx * 8 + wid; rb < MT; rb += nw * 4) {
;         f32x4 v[4][4];
; #pragma unroll
;         for (int j = 0; j < 4; ++j) {
;             const int row = rb + j * nw;
;             if (row < MT) {
;                 const float* x = a.out + (size_t)row * DM;
; #pragma unroll
;                 for (int i = 0; i < 4; ++i) v[j][i] = *(const f32x4*)(x + i * 256 + lane * 4);
.LBB0_2030:
	s_lshl_b32 s10, s12, 6
	buffer_inv sc1
	s_waitcnt vmcnt(0)
	s_add_i32 s0, s10, 0x10000
	s_add_i32 s10, s10, 0x10040
	v_ashrrev_i32_e32 v0, 6, v215
	v_add_u32_e32 v64, s0, v0
	v_cmp_gt_i32_e32 vcc, s10, v64
	s_and_saveexec_b64 s[0:1], vcc
	s_cbranch_execz .LBB0_2045
	v_lshlrev_b32_e32 v1, 4, v215
	v_and_b32_e32 v4, 64, v248
	v_and_b32_e32 v2, 0x3f0, v1
	v_add_u32_e32 v1, 64, v4
	v_xor_b32_e32 v4, 32, v248
	v_cmp_lt_i32_e32 vcc, v4, v1
	s_load_dwordx4 s[4:7], s[42:43], 0x100
	v_lshl_add_u32 v0, s16, 6, v0
	v_cndmask_b32_e32 v4, v248, v4, vcc
	v_lshlrev_b32_e32 v78, 2, v4
	v_xor_b32_e32 v4, 16, v248
	v_cmp_lt_i32_e32 vcc, v4, v1
	v_ashrrev_i32_e32 v65, 31, v64
	v_add_u32_e32 v0, 0xc208, v0
	v_cndmask_b32_e32 v4, v248, v4, vcc
	v_lshlrev_b32_e32 v79, 2, v4
	v_xor_b32_e32 v4, 8, v248
	v_cmp_lt_i32_e32 vcc, v4, v1
	s_mov_b64 s[0:1], 0x800
	v_mov_b32_e32 v3, 0
	v_cndmask_b32_e32 v4, v248, v4, vcc
	v_lshlrev_b32_e32 v80, 2, v4
	v_xor_b32_e32 v4, 4, v248
	v_cmp_lt_i32_e32 vcc, v4, v1
	s_waitcnt lgkmcnt(0)
	v_lshl_add_u64 v[66:67], s[6:7], 0, v[2:3]
	v_lshl_add_u64 v[68:69], s[4:5], 0, v[2:3]
	global_load_dwordx4 v[232:235], v[68:69], off
	global_load_dwordx4 v[236:239], v[68:69], off offset:1024
	global_load_dwordx4 v[240:243], v[68:69], off offset:2048
	global_load_dwordx4 v[244:247], v[68:69], off offset:3072
	v_cndmask_b32_e32 v4, v248, v4, vcc
	v_lshlrev_b32_e32 v81, 2, v4
	v_xor_b32_e32 v4, 2, v248
	v_cmp_lt_i32_e32 vcc, v4, v1
	s_mov_b32 s11, 0x800000
	s_mov_b64 s[8:9], 0x20000
	v_cndmask_b32_e32 v4, v248, v4, vcc
	v_lshlrev_b32_e32 v82, 2, v4
	v_xor_b32_e32 v4, 1, v248
	v_cmp_lt_i32_e32 vcc, v4, v1
	s_nop 1
	v_cndmask_b32_e32 v1, v248, v4, vcc
	v_lshlrev_b32_e32 v83, 2, v1
	v_lshlrev_b64 v[4:5], 12, v[64:65]
	v_ashrrev_i32_e32 v1, 31, v0
	v_or_b32_e32 v4, v4, v2
	v_lshlrev_b64 v[0:1], 12, v[0:1]
	v_lshl_add_u64 v[4:5], s[6:7], 0, v[4:5]
	v_or_b32_e32 v0, v0, v2
	v_lshl_add_u64 v[70:71], v[4:5], 0, s[0:1]
	v_lshl_add_u64 v[0:1], s[6:7], 0, v[0:1]
	s_mov_b64 s[0:1], 0xc00
	v_lshl_add_u64 v[72:73], v[0:1], 0, s[0:1]
	s_mov_b64 s[6:7], 0
	v_mov_b32_e32 v65, 0x358637bd
	s_branch .LBB0_2033

; __device__ __forceinline__ void final_phase(const Args& a, int wv, int row_lo, int row_hi, int bidx, int nblk) {
;     ...
;         for (int j = 0; j < 4; ++j) {
;             const int row = rb + j * nw;
;             if (row < MT) {
;                 float* x = a.out + (size_t)row * DM;
;                 float ss = 0.f;
; #pragma unroll
;                 for (int i = 0; i < 4; ++i) ss += v[j][i][0] * v[j][i][0] + v[j][i][1] * v[j][i][1] + v[j][i][2] * v[j][i][2] + v[j][i][3] * v[j][i][3];
;                 ss = wave_sum(ss);
;                 const float rstd = rsqrtf(ss * (1.f / 1024.f) + EPS);
; #pragma unroll
;                 for (int i = 0; i < 4; ++i) { const int c = i * 256 + lane * 4; const f32x4 g4 = *(const f32x4*)(g + c); __builtin_nontemporal_store(v[j][i] * rstd * g4, (f32x4*)(x + c)); }
;             }
.LBB0_2039:
	s_or_b64 exec, exec, s[4:5]
	s_waitcnt vmcnt(4)
	v_mov_b32_e32 v90, v61
	s_waitcnt vmcnt(3)
	v_mov_b32_e32 v91, v57
	v_mov_b32_e32 v88, v60
	v_mov_b32_e32 v89, v56
	s_waitcnt vmcnt(2)
	v_mov_b32_e32 v98, v53
	s_waitcnt vmcnt(1)
	v_mov_b32_e32 v99, v49
	v_pk_mul_f32 v[90:91], v[90:91], v[90:91]
	v_mov_b32_e32 v92, v62
	v_mov_b32_e32 v93, v58
	v_mov_b32_e32 v96, v52
	v_mov_b32_e32 v97, v48
	v_pk_mul_f32 v[98:99], v[98:99], v[98:99]
	v_pk_fma_f32 v[88:89], v[88:89], v[88:89], v[90:91]
	v_mov_b32_e32 v94, v63
	v_mov_b32_e32 v95, v59
	v_mov_b32_e32 v100, v54
	v_mov_b32_e32 v101, v50
	v_pk_fma_f32 v[90:91], v[96:97], v[96:97], v[98:99]
	v_pk_fma_f32 v[88:89], v[92:93], v[92:93], v[88:89]
	v_mov_b32_e32 v102, v55
	v_mov_b32_e32 v103, v51
	v_pk_fma_f32 v[90:91], v[100:101], v[100:101], v[90:91]
	v_pk_fma_f32 v[88:89], v[94:95], v[94:95], v[88:89]
	v_pk_fma_f32 v[90:91], v[102:103], v[102:103], v[90:91]
	v_add_f32_e32 v88, v88, v89
	v_add_f32_e32 v88, v88, v90
	v_add_f32_e32 v88, v88, v91
	ds_bpermute_b32 v89, v78, v88
	s_waitcnt lgkmcnt(0)
	v_add_f32_e32 v88, v88, v89
	ds_bpermute_b32 v89, v79, v88
	s_waitcnt lgkmcnt(0)
	v_add_f32_e32 v88, v88, v89
	ds_bpermute_b32 v89, v80, v88
	s_waitcnt lgkmcnt(0)
	v_add_f32_e32 v88, v88, v89
	ds_bpermute_b32 v89, v81, v88
	s_waitcnt lgkmcnt(0)
	v_add_f32_e32 v88, v88, v89
	ds_bpermute_b32 v89, v82, v88
	s_waitcnt lgkmcnt(0)
	v_add_f32_e32 v88, v88, v89
	ds_bpermute_b32 v89, v83, v88
	s_waitcnt lgkmcnt(0)
	v_add_f32_e32 v88, v88, v89
	v_fmamk_f32 v88, v88, 0x3a800000, v65
	v_mul_f32_e32 v89, 0x4b800000, v88
	v_cmp_gt_f32_e64 s[4:5], s11, v88
	s_nop 1
	v_cndmask_b32_e64 v88, v88, v89, s[4:5]
	v_rsq_f32_e32 v88, v88
	s_nop 0
	v_mul_f32_e32 v89, 0x45800000, v88
	v_cndmask_b32_e64 v88, v88, v89, s[4:5]
	v_pk_mul_f32 v[60:61], v[60:61], v[88:89] op_sel_hi:[1,0]
	v_pk_mul_f32 v[62:63], v[62:63], v[88:89] op_sel_hi:[1,0]
	v_pk_mul_f32 v[58:59], v[58:59], v[88:89] op_sel_hi:[1,0]
	v_pk_mul_f32 v[56:57], v[56:57], v[88:89] op_sel_hi:[1,0]
	s_waitcnt vmcnt(0)
	v_pk_mul_f32 v[62:63], v[234:235], v[62:63]
	v_pk_mul_f32 v[60:61], v[232:233], v[60:61]
	global_store_dwordx4 v[70:71], v[60:63], off offset:-2048 nt
	v_pk_mul_f32 v[54:55], v[54:55], v[88:89] op_sel_hi:[1,0]
	v_pk_mul_f32 v[52:53], v[52:53], v[88:89] op_sel_hi:[1,0]
	v_pk_mul_f32 v[50:51], v[50:51], v[88:89] op_sel_hi:[1,0]
	v_pk_mul_f32 v[48:49], v[48:49], v[88:89] op_sel_hi:[1,0]
	v_pk_mul_f32 v[56:57], v[236:237], v[56:57]
	v_pk_mul_f32 v[58:59], v[238:239], v[58:59]
	global_store_dwordx4 v[70:71], v[56:59], off offset:-1024 nt
	v_pk_mul_f32 v[52:53], v[240:241], v[52:53]
	v_pk_mul_f32 v[54:55], v[242:243], v[54:55]
	global_store_dwordx4 v[70:71], v[52:55], off nt
	v_pk_mul_f32 v[48:49], v[244:245], v[48:49]
	v_pk_mul_f32 v[50:51], v[246:247], v[50:51]
	global_store_dwordx4 v[70:71], v[48:51], off offset:1024 nt
	s_and_saveexec_b64 s[4:5], s[2:3]
	s_cbranch_execz .LBB0_2042
	v_mov_b32_e32 v54, v25
	v_mov_b32_e32 v55, v29
	v_mov_b32_e32 v52, v24
	v_mov_b32_e32 v53, v28
	v_mov_b32_e32 v62, v17
	v_mov_b32_e32 v63, v21
	v_pk_mul_f32 v[54:55], v[54:55], v[54:55]
	v_mov_b32_e32 v56, v26
	v_mov_b32_e32 v57, v30
	v_mov_b32_e32 v60, v16
	v_mov_b32_e32 v61, v20
	v_pk_mul_f32 v[62:63], v[62:63], v[62:63]
	v_pk_fma_f32 v[52:53], v[52:53], v[52:53], v[54:55]
	v_mov_b32_e32 v58, v27
	v_mov_b32_e32 v59, v31
	v_mov_b32_e32 v84, v18
	v_mov_b32_e32 v85, v22
	v_pk_fma_f32 v[54:55], v[60:61], v[60:61], v[62:63]
	v_pk_fma_f32 v[52:53], v[56:57], v[56:57], v[52:53]
	v_mov_b32_e32 v86, v19
	v_mov_b32_e32 v87, v23
	v_pk_fma_f32 v[54:55], v[84:85], v[84:85], v[54:55]
	v_pk_fma_f32 v[52:53], v[58:59], v[58:59], v[52:53]
	v_pk_fma_f32 v[54:55], v[86:87], v[86:87], v[54:55]
	v_add_f32_e32 v52, v52, v53
	v_add_f32_e32 v52, v55, v52
	v_add_f32_e32 v52, v54, v52
	ds_bpermute_b32 v53, v78, v52
	s_waitcnt lgkmcnt(0)
	v_add_f32_e32 v52, v52, v53
	ds_bpermute_b32 v53, v79, v52
	s_waitcnt lgkmcnt(0)
	v_add_f32_e32 v52, v52, v53
	ds_bpermute_b32 v53, v80, v52
	s_waitcnt lgkmcnt(0)
	v_add_f32_e32 v52, v52, v53
	ds_bpermute_b32 v53, v81, v52
	s_waitcnt lgkmcnt(0)
	v_add_f32_e32 v52, v52, v53
	ds_bpermute_b32 v53, v82, v52
	s_waitcnt lgkmcnt(0)
	v_add_f32_e32 v52, v52, v53
	ds_bpermute_b32 v53, v83, v52
	s_waitcnt lgkmcnt(0)
	v_add_f32_e32 v52, v52, v53
	v_fmamk_f32 v52, v52, 0x3a800000, v65
	v_mul_f32_e32 v53, 0x4b800000, v52
	v_cmp_gt_f32_e64 s[2:3], s11, v52
	s_nop 1
	v_cndmask_b32_e64 v52, v52, v53, s[2:3]
	v_rsq_f32_e32 v52, v52
	s_nop 0
	v_mul_f32_e32 v53, 0x45800000, v52
	v_cndmask_b32_e64 v52, v52, v53, s[2:3]
	v_pk_mul_f32 v[54:55], v[28:29], v[52:53] op_sel_hi:[1,0]
	v_pk_mul_f32 v[56:57], v[30:31], v[52:53] op_sel_hi:[1,0]
	v_pk_mul_f32 v[48:49], v[232:233], v[54:55]
	v_pk_mul_f32 v[50:51], v[234:235], v[56:57]
	global_store_dwordx4 v[72:73], v[48:51], off offset:-3072 nt
	v_pk_mul_f32 v[54:55], v[26:27], v[52:53] op_sel_hi:[1,0]
	v_pk_mul_f32 v[56:57], v[24:25], v[52:53] op_sel_hi:[1,0]
	v_pk_mul_f32 v[50:51], v[238:239], v[54:55]
	v_pk_mul_f32 v[48:49], v[236:237], v[56:57]
	global_store_dwordx4 v[72:73], v[48:51], off offset:-2048 nt
	v_pk_mul_f32 v[54:55], v[22:23], v[52:53] op_sel_hi:[1,0]
	v_pk_mul_f32 v[56:57], v[20:21], v[52:53] op_sel_hi:[1,0]
	v_pk_mul_f32 v[50:51], v[242:243], v[54:55]
	v_pk_mul_f32 v[48:49], v[240:241], v[56:57]
	global_store_dwordx4 v[72:73], v[48:51], off offset:-1024 nt
	v_pk_mul_f32 v[54:55], v[18:19], v[52:53] op_sel_hi:[1,0]
	v_pk_mul_f32 v[52:53], v[16:17], v[52:53] op_sel_hi:[1,0]
	v_pk_mul_f32 v[50:51], v[246:247], v[54:55]
	v_pk_mul_f32 v[48:49], v[244:245], v[52:53]
	global_store_dwordx4 v[72:73], v[48:51], off nt
	s_or_b64 exec, exec, s[4:5]
	s_and_saveexec_b64 s[2:3], s[0:1]
	s_cbranch_execnz .LBB0_2043

; __device__ __forceinline__ void final_phase(const Args& a, int wv, int row_lo, int row_hi, int bidx, int nblk) {
;     ...
;         for (int j = 0; j < 4; ++j) {
;             const int row = rb + j * nw;
;             if (row < MT) {
;                 float* x = a.out + (size_t)row * DM;
;                 float ss = 0.f;
; #pragma unroll
;                 for (int i = 0; i < 4; ++i) ss += v[j][i][0] * v[j][i][0] + v[j][i][1] * v[j][i][1] + v[j][i][2] * v[j][i][2] + v[j][i][3] * v[j][i][3];
;                 ss = wave_sum(ss);
;                 const float rstd = rsqrtf(ss * (1.f / 1024.f) + EPS);
; #pragma unroll
;                 for (int i = 0; i < 4; ++i) { const int c = i * 256 + lane * 4; const f32x4 g4 = *(const f32x4*)(g + c); __builtin_nontemporal_store(v[j][i] * rstd * g4, (f32x4*)(x + c)); }
;             }
.LBB0_2043:
	v_mov_b32_e32 v54, v41
	v_mov_b32_e32 v55, v45
	v_mov_b32_e32 v52, v40
	v_mov_b32_e32 v53, v44
	v_mov_b32_e32 v62, v33
	v_mov_b32_e32 v63, v37
	v_pk_mul_f32 v[54:55], v[54:55], v[54:55]
	v_mov_b32_e32 v56, v42
	v_mov_b32_e32 v57, v46
	v_mov_b32_e32 v60, v32
	v_mov_b32_e32 v61, v36
	v_pk_mul_f32 v[62:63], v[62:63], v[62:63]
	v_pk_fma_f32 v[52:53], v[52:53], v[52:53], v[54:55]
	v_mov_b32_e32 v58, v43
	v_mov_b32_e32 v59, v47
	v_mov_b32_e32 v84, v34
	v_mov_b32_e32 v85, v38
	v_pk_fma_f32 v[54:55], v[60:61], v[60:61], v[62:63]
	v_pk_fma_f32 v[52:53], v[56:57], v[56:57], v[52:53]
	v_mov_b32_e32 v86, v35
	v_mov_b32_e32 v87, v39
	v_pk_fma_f32 v[54:55], v[84:85], v[84:85], v[54:55]
	v_pk_fma_f32 v[52:53], v[58:59], v[58:59], v[52:53]
	v_pk_fma_f32 v[54:55], v[86:87], v[86:87], v[54:55]
	v_add_f32_e32 v52, v52, v53
	v_add_f32_e32 v52, v55, v52
	v_add_f32_e32 v52, v54, v52
	ds_bpermute_b32 v53, v78, v52
	s_waitcnt lgkmcnt(0)
	v_add_f32_e32 v52, v52, v53
	ds_bpermute_b32 v53, v79, v52
	s_waitcnt lgkmcnt(0)
	v_add_f32_e32 v52, v52, v53
	ds_bpermute_b32 v53, v80, v52
	s_waitcnt lgkmcnt(0)
	v_add_f32_e32 v52, v52, v53
	ds_bpermute_b32 v53, v81, v52
	s_waitcnt lgkmcnt(0)
	v_add_f32_e32 v52, v52, v53
	ds_bpermute_b32 v53, v82, v52
	s_waitcnt lgkmcnt(0)
	v_add_f32_e32 v52, v52, v53
	ds_bpermute_b32 v53, v83, v52
	s_waitcnt lgkmcnt(0)
	v_add_f32_e32 v52, v52, v53
	v_fmamk_f32 v52, v52, 0x3a800000, v65
	v_mul_f32_e32 v53, 0x4b800000, v52
	v_cmp_gt_f32_e64 s[0:1], s11, v52
	s_nop 1
	v_cndmask_b32_e64 v52, v52, v53, s[0:1]
	v_rsq_f32_e32 v54, v52
	v_lshlrev_b64 v[52:53], 12, v[76:77]
	v_lshl_add_u64 v[52:53], v[66:67], 0, v[52:53]
	v_mul_f32_e32 v55, 0x45800000, v54
	v_cndmask_b32_e64 v54, v54, v55, s[0:1]
	v_pk_mul_f32 v[56:57], v[44:45], v[54:55] op_sel_hi:[1,0]
	v_pk_mul_f32 v[58:59], v[46:47], v[54:55] op_sel_hi:[1,0]
	v_pk_mul_f32 v[48:49], v[232:233], v[56:57]
	v_pk_mul_f32 v[50:51], v[234:235], v[58:59]
	global_store_dwordx4 v[52:53], v[48:51], off nt
	v_pk_mul_f32 v[56:57], v[42:43], v[54:55] op_sel_hi:[1,0]
	v_pk_mul_f32 v[58:59], v[40:41], v[54:55] op_sel_hi:[1,0]
	v_pk_mul_f32 v[50:51], v[238:239], v[56:57]
	v_pk_mul_f32 v[48:49], v[236:237], v[58:59]
	global_store_dwordx4 v[52:53], v[48:51], off offset:1024 nt
	v_pk_mul_f32 v[56:57], v[38:39], v[54:55] op_sel_hi:[1,0]
	v_pk_mul_f32 v[58:59], v[36:37], v[54:55] op_sel_hi:[1,0]
	v_pk_mul_f32 v[50:51], v[242:243], v[56:57]
	v_pk_mul_f32 v[48:49], v[240:241], v[58:59]
	global_store_dwordx4 v[52:53], v[48:51], off offset:2048 nt
	v_pk_mul_f32 v[56:57], v[34:35], v[54:55] op_sel_hi:[1,0]
	v_pk_mul_f32 v[54:55], v[32:33], v[54:55] op_sel_hi:[1,0]
	v_pk_mul_f32 v[50:51], v[246:247], v[56:57]
	v_pk_mul_f32 v[48:49], v[244:245], v[54:55]
	global_store_dwordx4 v[52:53], v[48:51], off offset:3072 nt
	s_or_b64 exec, exec, s[2:3]
	s_and_saveexec_b64 s[0:1], vcc
	s_cbranch_execz .LBB0_2032
.LBB0_2044:
	v_mov_b32_e32 v54, v9
	v_mov_b32_e32 v55, v13
	v_mov_b32_e32 v52, v8
	v_mov_b32_e32 v53, v12
	v_mov_b32_e32 v62, v1
	v_mov_b32_e32 v63, v5
	v_pk_mul_f32 v[54:55], v[54:55], v[54:55]
	v_mov_b32_e32 v56, v10
	v_mov_b32_e32 v57, v14
	v_mov_b32_e32 v60, v0
	v_mov_b32_e32 v61, v4
	v_pk_mul_f32 v[62:63], v[62:63], v[62:63]
	v_pk_fma_f32 v[52:53], v[52:53], v[52:53], v[54:55]
	v_mov_b32_e32 v58, v11
	v_mov_b32_e32 v59, v15
	v_mov_b32_e32 v76, v2
	v_mov_b32_e32 v77, v6
	v_pk_fma_f32 v[54:55], v[60:61], v[60:61], v[62:63]
	v_pk_fma_f32 v[52:53], v[56:57], v[56:57], v[52:53]
	v_mov_b32_e32 v84, v3
	v_mov_b32_e32 v85, v7
	v_pk_fma_f32 v[54:55], v[76:77], v[76:77], v[54:55]
	v_pk_fma_f32 v[52:53], v[58:59], v[58:59], v[52:53]
	v_pk_fma_f32 v[54:55], v[84:85], v[84:85], v[54:55]
	v_add_f32_e32 v52, v52, v53
	v_add_f32_e32 v52, v55, v52
	v_add_f32_e32 v52, v54, v52
	ds_bpermute_b32 v53, v78, v52
	s_waitcnt lgkmcnt(0)
	v_add_f32_e32 v52, v52, v53
	ds_bpermute_b32 v53, v79, v52
	s_waitcnt lgkmcnt(0)
	v_add_f32_e32 v52, v52, v53
	ds_bpermute_b32 v53, v80, v52
	s_waitcnt lgkmcnt(0)
	v_add_f32_e32 v52, v52, v53
	ds_bpermute_b32 v53, v81, v52
	s_waitcnt lgkmcnt(0)
	v_add_f32_e32 v52, v52, v53
	ds_bpermute_b32 v53, v82, v52
	s_waitcnt lgkmcnt(0)
	v_add_f32_e32 v52, v52, v53
	ds_bpermute_b32 v53, v83, v52
	s_waitcnt lgkmcnt(0)
	v_add_f32_e32 v52, v52, v53
	v_fmamk_f32 v52, v52, 0x3a800000, v65
	v_mul_f32_e32 v53, 0x4b800000, v52
	v_cmp_gt_f32_e32 vcc, s11, v52
	s_nop 1
	v_cndmask_b32_e32 v52, v52, v53, vcc
	v_rsq_f32_e32 v54, v52
	v_lshlrev_b64 v[52:53], 12, v[74:75]
	v_lshl_add_u64 v[52:53], v[66:67], 0, v[52:53]
	v_mul_f32_e32 v55, 0x45800000, v54
	v_cndmask_b32_e32 v54, v54, v55, vcc
	v_pk_mul_f32 v[56:57], v[12:13], v[54:55] op_sel_hi:[1,0]
	v_pk_mul_f32 v[58:59], v[14:15], v[54:55] op_sel_hi:[1,0]
	v_pk_mul_f32 v[48:49], v[232:233], v[56:57]
	v_pk_mul_f32 v[50:51], v[234:235], v[58:59]
	global_store_dwordx4 v[52:53], v[48:51], off nt
	v_pk_mul_f32 v[56:57], v[10:11], v[54:55] op_sel_hi:[1,0]
	v_pk_mul_f32 v[58:59], v[8:9], v[54:55] op_sel_hi:[1,0]
	v_pk_mul_f32 v[50:51], v[238:239], v[56:57]
	v_pk_mul_f32 v[48:49], v[236:237], v[58:59]
	global_store_dwordx4 v[52:53], v[48:51], off offset:1024 nt
	v_pk_mul_f32 v[56:57], v[6:7], v[54:55] op_sel_hi:[1,0]
	v_pk_mul_f32 v[58:59], v[4:5], v[54:55] op_sel_hi:[1,0]
	v_pk_mul_f32 v[50:51], v[242:243], v[56:57]
	v_pk_mul_f32 v[48:49], v[240:241], v[58:59]
	global_store_dwordx4 v[52:53], v[48:51], off offset:2048 nt
	v_pk_mul_f32 v[56:57], v[2:3], v[54:55] op_sel_hi:[1,0]
	v_pk_mul_f32 v[54:55], v[0:1], v[54:55] op_sel_hi:[1,0]
	v_pk_mul_f32 v[50:51], v[246:247], v[56:57]
	v_pk_mul_f32 v[48:49], v[244:245], v[54:55]
	global_store_dwordx4 v[52:53], v[48:51], off offset:3072 nt
	s_branch .LBB0_2032
